# s_setprio 3 for the GLA scan state waves (over v31 GLA decay-read batching)
# baseline (speedup 1.0000x reference)
; __device__ __forceinline__ int opaque_tid() { int t = threadIdx.x; asm volatile("" : "+v"(t)); return t; }
; #define LAS __attribute__((address_space(3)))
; #define BAR_LDS() do { asm volatile("s_waitcnt lgkmcnt(0)" ::: "memory"); __builtin_amdgcn_s_barrier(); asm volatile("" ::: "memory"); } while (0)
; template <int PASS>
; __device__ __forceinline__ void gla_scan3(LAS unsigned char* lds, bf16_t* P  , const bf16_t* QM, const bf16_t* KM, const bf16_t* AQ, const float* EL, bf16_t* OB  , float* SEND, float* DSUM) {
;     ...
;             BAR_LDS();
;             for (int step = lo; step < hi; ++step) {
;                 const int lane = opaque_tid() & 63, r = lane & 31, h = lane >> 5;
;                 LAS unsigned char* base = lds + ((step - lo) & 1) * GL_DIR;
;                 LAS bf16_t* Qm = (LAS bf16_t*)(base + GL_QM); LAS bf16_t* Km = (LAS bf16_t*)(base + GL_KM); LAS bf16_t* Vb = (LAS bf16_t*)(base + GL_VB); LAS bf16_t* Ab = (LAS bf16_t*)(base + GL_AB);
;                 LAS float* el = (LAS float*)(base + GL_EL);
;                 int rb; bool f_; dn_step_rb(step, dir, b, rb, f_);
.LBB0_265:
	s_waitcnt lgkmcnt(0)
	s_barrier
	s_cmp_ge_u32 s60, s57
	s_cbranch_scc1 .LBB0_288
	s_sub_i32 s62, 0x103, s56
	s_cmp_eq_u32 s59, 0
	s_cselect_b64 s[44:45], -1, 0
	s_cmp_lg_u32 s59, 0
	s_cselect_b64 s[46:47], -1, 0
	s_lshl_b32 s0, s53, 8
	s_lshl_b32 s1, s52, 7
	s_lshl_b32 s65, s58, 2
	s_or_b32 s0, s0, s1
	s_mov_b32 s63, 0
	s_lshl_b32 s64, s58, 8
	s_addk_i32 s65, 0x200
	s_or_b32 s66, s0, s18
	s_setprio 3
	s_branch .LBB0_268
